# L1 invalidate (buffer_inv sc1) issued at barrier arrival instead of after release in grid/xcc barriers; removed unneeded invalidate in P6 row-stat exchange
# speedup vs baseline: 1.0123x; 1.0099x over previous
.LBB0_61:
	s_or_b64 exec, exec, s[16:17]
	buffer_inv sc1
	v_cvt_f32_u32_e32 v4, v2
	s_waitcnt vmcnt(1)
	v_readfirstlane_b32 s12, v3
	v_sub_u32_e32 v3, 0, v2
	v_rcp_iflag_f32_e32 v4, v4
	v_add_u32_e32 v5, s12, v1
	v_mul_f32_e32 v4, 0x4f7ffffe, v4
	v_cvt_u32_f32_e32 v4, v4
	v_mul_lo_u32 v1, v3, v4
	v_mul_hi_u32 v1, v4, v1
	v_add_u32_e32 v1, v4, v1
	v_mul_hi_u32 v1, v5, v1
	v_mul_lo_u32 v3, v1, v2
	v_sub_u32_e32 v3, v5, v3
	v_add_u32_e32 v4, 1, v1
	v_cmp_ge_u32_e32 vcc, v3, v2
	s_nop 1
	v_cndmask_b32_e32 v1, v1, v4, vcc
	v_sub_u32_e32 v4, v3, v2
	v_cndmask_b32_e32 v3, v3, v4, vcc
	v_add_u32_e32 v4, 1, v1
	v_cmp_ge_u32_e32 vcc, v3, v2
	v_add_u32_e32 v3, 1, v5
	s_nop 0
	v_cndmask_b32_e32 v1, v1, v4, vcc
	v_mul_lo_u32 v4, v2, v1
	v_add_u32_e32 v2, v4, v2
	v_cmp_ne_u32_e32 vcc, v3, v2
	s_and_saveexec_b64 s[12:13], vcc
	s_xor_b64 s[12:13], exec, s[12:13]
	s_cbranch_execz .LBB0_75
	s_waitcnt lgkmcnt(0)
	v_mov_b32_e32 v0, 0x2000
	global_load_dword v0, v0, s[8:9] offset:1024 sc1
	s_add_u32 s20, s8, 0x2400
	s_addc_u32 s21, s9, 0
	s_waitcnt vmcnt(0)
	v_cmp_eq_u32_e32 vcc, v0, v1
	s_and_saveexec_b64 s[16:17], vcc
	s_cbranch_execz .LBB0_74
	s_add_u32 s18, s6, 0x4200
	s_addc_u32 s19, s7, 0
	s_mov_b32 s34, 1
	s_mov_b64 s[22:23], 0
	v_mov_b32_e32 v0, 0
	s_branch .LBB0_65

.LBB0_74:
	s_or_b64 exec, exec, s[16:17]
	s_waitcnt vmcnt(0)
	s_waitcnt vmcnt(0)

.LBB0_627:
	s_or_b64 exec, exec, s[12:13]
	buffer_inv sc1
	s_waitcnt vmcnt(1)
	v_readfirstlane_b32 s8, v1
	s_add_u32 s6, s6, 0xd000
	s_addc_u32 s7, s7, 0
	v_add_u32_e32 v0, s8, v0
	v_and_b32_e32 v1, 31, v0
	v_cmp_ne_u32_e32 vcc, 31, v1
	s_and_saveexec_b64 s[8:9], vcc
	s_xor_b64 s[8:9], exec, s[8:9]
	s_cbranch_execz .LBB0_642
	v_lshrrev_b32_e32 v0, 5, v0
	s_mov_b32 s30, 0x400001
	s_mov_b64 s[12:13], 0
	v_mov_b32_e32 v1, 0
	s_branch .LBB0_635

.LBB0_646:
	s_or_b64 exec, exec, s[8:9]
	s_waitcnt vmcnt(0)
	s_waitcnt vmcnt(0)

.LBB0_839:
	s_or_b64 exec, exec, s[18:19]
	buffer_inv sc1
	s_waitcnt vmcnt(1)
	v_readfirstlane_b32 s16, v1
	s_add_u32 s8, s8, 0xd000
	s_addc_u32 s9, s9, 0
	v_add_u32_e32 v0, s16, v0
	v_and_b32_e32 v1, 31, v0
	v_cmp_ne_u32_e32 vcc, 31, v1
	s_and_saveexec_b64 s[16:17], vcc
	s_xor_b64 s[16:17], exec, s[16:17]
	s_cbranch_execz .LBB0_853
	v_lshrrev_b32_e32 v0, 5, v0
	s_mov_b32 s36, 0x400001
	s_mov_b64 s[18:19], 0
	v_mov_b32_e32 v1, 0
	s_branch .LBB0_846

.LBB0_878:
	s_or_b64 exec, exec, s[20:21]
	buffer_inv sc1
	v_cvt_f32_u32_e32 v4, v2
	s_waitcnt vmcnt(1)
	v_readfirstlane_b32 s18, v3
	v_sub_u32_e32 v3, 0, v2
	v_rcp_iflag_f32_e32 v4, v4
	v_add_u32_e32 v5, s18, v1
	v_mul_f32_e32 v4, 0x4f7ffffe, v4
	v_cvt_u32_f32_e32 v4, v4
	v_mul_lo_u32 v1, v3, v4
	v_mul_hi_u32 v1, v4, v1
	v_add_u32_e32 v1, v4, v1
	v_mul_hi_u32 v1, v5, v1
	v_mul_lo_u32 v3, v1, v2
	v_sub_u32_e32 v3, v5, v3
	v_add_u32_e32 v4, 1, v1
	v_cmp_ge_u32_e32 vcc, v3, v2
	s_nop 1
	v_cndmask_b32_e32 v1, v1, v4, vcc
	v_sub_u32_e32 v4, v3, v2
	v_cndmask_b32_e32 v3, v3, v4, vcc
	v_add_u32_e32 v4, 1, v1
	v_cmp_ge_u32_e32 vcc, v3, v2
	v_add_u32_e32 v3, 1, v5
	s_nop 0
	v_cndmask_b32_e32 v1, v1, v4, vcc
	v_mul_lo_u32 v4, v2, v1
	v_add_u32_e32 v2, v4, v2
	v_cmp_ne_u32_e32 vcc, v3, v2
	s_and_saveexec_b64 s[18:19], vcc
	s_xor_b64 s[18:19], exec, s[18:19]
	s_cbranch_execz .LBB0_892
	s_waitcnt lgkmcnt(0)
	v_mov_b32_e32 v0, 0x2000
	global_load_dword v0, v0, s[16:17] offset:1024 sc1
	s_add_u32 s24, s16, 0x2400
	s_addc_u32 s25, s17, 0
	s_waitcnt vmcnt(0)
	v_cmp_eq_u32_e32 vcc, v0, v1
	s_and_saveexec_b64 s[20:21], vcc
	s_cbranch_execz .LBB0_891
	s_add_u32 s22, s8, 0x4200
	s_addc_u32 s23, s9, 0
	s_mov_b32 s38, 1
	s_mov_b64 s[26:27], 0
	v_mov_b32_e32 v0, 0
	s_branch .LBB0_882

.LBB0_891:
	s_or_b64 exec, exec, s[20:21]
	s_waitcnt vmcnt(0)
	s_waitcnt vmcnt(0)

.LBB0_969:
	s_or_b64 exec, exec, s[16:17]
	buffer_inv sc1
	s_waitcnt vmcnt(1)
	v_readfirstlane_b32 s8, v1
	s_add_u32 s6, s6, 0xd000
	s_addc_u32 s7, s7, 0
	v_add_u32_e32 v0, s8, v0
	v_and_b32_e32 v1, 31, v0
	v_cmp_ne_u32_e32 vcc, 31, v1
	s_and_saveexec_b64 s[8:9], vcc
	s_xor_b64 s[8:9], exec, s[8:9]
	s_cbranch_execz .LBB0_990
	v_lshrrev_b32_e32 v0, 5, v0
	s_mov_b32 s34, 0x400001
	s_mov_b64 s[16:17], 0
	v_mov_b32_e32 v1, 0
	s_branch .LBB0_977

.LBB0_1016:
	s_or_b64 exec, exec, s[18:19]
	buffer_inv sc1
	v_cvt_f32_u32_e32 v4, v2
	s_waitcnt vmcnt(1)
	v_readfirstlane_b32 s16, v3
	v_sub_u32_e32 v3, 0, v2
	v_rcp_iflag_f32_e32 v4, v4
	v_add_u32_e32 v5, s16, v1
	v_mul_f32_e32 v4, 0x4f7ffffe, v4
	v_cvt_u32_f32_e32 v4, v4
	v_mul_lo_u32 v1, v3, v4
	v_mul_hi_u32 v1, v4, v1
	v_add_u32_e32 v1, v4, v1
	v_mul_hi_u32 v1, v5, v1
	v_mul_lo_u32 v3, v1, v2
	v_sub_u32_e32 v3, v5, v3
	v_add_u32_e32 v4, 1, v1
	v_cmp_ge_u32_e32 vcc, v3, v2
	s_nop 1
	v_cndmask_b32_e32 v1, v1, v4, vcc
	v_sub_u32_e32 v4, v3, v2
	v_cndmask_b32_e32 v3, v3, v4, vcc
	v_add_u32_e32 v4, 1, v1
	v_cmp_ge_u32_e32 vcc, v3, v2
	v_add_u32_e32 v3, 1, v5
	s_nop 0
	v_cndmask_b32_e32 v1, v1, v4, vcc
	v_mul_lo_u32 v4, v2, v1
	v_add_u32_e32 v2, v4, v2
	v_cmp_ne_u32_e32 vcc, v3, v2
	s_and_saveexec_b64 s[16:17], vcc
	s_xor_b64 s[16:17], exec, s[16:17]
	s_cbranch_execz .LBB0_1030
	s_waitcnt lgkmcnt(0)
	v_mov_b32_e32 v0, 0x2000
	global_load_dword v0, v0, s[8:9] offset:1024 sc1
	s_add_u32 s22, s8, 0x2400
	s_addc_u32 s23, s9, 0
	s_waitcnt vmcnt(0)
	v_cmp_eq_u32_e32 vcc, v0, v1
	s_and_saveexec_b64 s[18:19], vcc
	s_cbranch_execz .LBB0_1029
	s_add_u32 s20, s6, 0x4200
	s_addc_u32 s21, s7, 0
	s_mov_b32 s36, 1
	s_mov_b64 s[24:25], 0
	v_mov_b32_e32 v0, 0
	s_branch .LBB0_1020

.LBB0_1029:
	s_or_b64 exec, exec, s[18:19]
	s_waitcnt vmcnt(0)
	s_waitcnt vmcnt(0)

.LBB0_1173:
	s_waitcnt lgkmcnt(0)
.LBB0_1174:
	s_waitcnt vmcnt(0) lgkmcnt(0)
	s_barrier
	s_and_saveexec_b64 s[12:13], s[4:5]
	s_cbranch_execz .LBB0_1176
	v_lshl_add_u64 v[130:131], v[130:131], 4, s[16:17]
	global_load_dword v132, v[130:131], off sc1
	global_load_dword v134, v[130:131], off offset:4 sc1
	global_load_dword v135, v[130:131], off offset:8 sc1
	s_nop 0
	global_load_dword v130, v[130:131], off offset:12 sc1
	v_mov_b32_e32 v131, 0x358637bd
	s_mov_b32 s4, 0xf800000
	s_waitcnt vmcnt(3)
	v_add_f32_e32 v132, 0, v132
	s_waitcnt vmcnt(2)
	v_add_f32_e32 v132, v132, v134
	s_waitcnt vmcnt(1)
	v_add_f32_e32 v132, v132, v135
	s_waitcnt vmcnt(0)
	v_add_f32_e32 v130, v132, v130
	v_fmac_f32_e32 v131, 0x3a800000, v130
	v_mul_f32_e32 v130, 0x4f800000, v131
	v_cmp_gt_f32_e32 vcc, s4, v131
	v_mov_b32_e32 v132, 0x260
	s_nop 0
	v_cndmask_b32_e32 v130, v131, v130, vcc
	v_sqrt_f32_e32 v131, v130
	s_nop 0
	v_add_u32_e32 v134, -1, v131
	v_add_u32_e32 v135, 1, v131
	v_fma_f32 v136, -v134, v131, v130
	v_fma_f32 v137, -v135, v131, v130
	v_cmp_ge_f32_e64 s[4:5], 0, v136
	s_nop 1
	v_cndmask_b32_e64 v131, v131, v134, s[4:5]
	v_cmp_lt_f32_e64 s[4:5], 0, v137
	s_nop 1
	v_cndmask_b32_e64 v131, v131, v135, s[4:5]
	v_mul_f32_e32 v134, 0x37800000, v131
	v_cndmask_b32_e32 v131, v131, v134, vcc
	v_cmp_class_f32_e32 vcc, v130, v132
	s_nop 1
	v_cndmask_b32_e32 v130, v131, v130, vcc
	v_div_scale_f32 v131, s[4:5], v130, v130, 1.0
	v_rcp_f32_e32 v132, v131
	v_div_scale_f32 v134, vcc, 1.0, v130, 1.0
	v_fma_f32 v135, -v131, v132, 1.0
	v_fmac_f32_e32 v132, v135, v132
	v_mul_f32_e32 v135, v134, v132
	v_fma_f32 v136, -v131, v135, v134
	v_fmac_f32_e32 v135, v136, v132
	v_fma_f32 v131, -v131, v135, v134
	v_div_fmas_f32 v131, v131, v132, v135
	v_div_fixup_f32 v130, v131, v130, 1.0
	v_lshl_add_u32 v131, v133, 2, 0
	ds_write_b32 v131, v130 offset:4096

.LBB0_1199:
	s_or_b64 exec, exec, s[12:13]
	buffer_inv sc1
	v_cvt_f32_u32_e32 v4, v2
	s_waitcnt vmcnt(1)
	v_readfirstlane_b32 s10, v3
	v_sub_u32_e32 v3, 0, v2
	v_rcp_iflag_f32_e32 v4, v4
	v_add_u32_e32 v5, s10, v1
	v_mul_f32_e32 v4, 0x4f7ffffe, v4
	v_cvt_u32_f32_e32 v4, v4
	v_mul_lo_u32 v1, v3, v4
	v_mul_hi_u32 v1, v4, v1
	v_add_u32_e32 v1, v4, v1
	v_mul_hi_u32 v1, v5, v1
	v_mul_lo_u32 v3, v1, v2
	v_sub_u32_e32 v3, v5, v3
	v_add_u32_e32 v4, 1, v1
	v_cmp_ge_u32_e32 vcc, v3, v2
	s_nop 1
	v_cndmask_b32_e32 v1, v1, v4, vcc
	v_sub_u32_e32 v4, v3, v2
	v_cndmask_b32_e32 v3, v3, v4, vcc
	v_add_u32_e32 v4, 1, v1
	v_cmp_ge_u32_e32 vcc, v3, v2
	v_add_u32_e32 v3, 1, v5
	s_nop 0
	v_cndmask_b32_e32 v1, v1, v4, vcc
	v_mul_lo_u32 v4, v2, v1
	v_add_u32_e32 v2, v4, v2
	v_cmp_ne_u32_e32 vcc, v3, v2
	s_and_saveexec_b64 s[10:11], vcc
	s_xor_b64 s[10:11], exec, s[10:11]
	s_cbranch_execz .LBB0_1213
	s_waitcnt lgkmcnt(0)
	v_mov_b32_e32 v0, 0x2000
	global_load_dword v0, v0, s[8:9] offset:1024 sc1
	s_add_u32 s16, s8, 0x2400
	s_addc_u32 s17, s9, 0
	s_waitcnt vmcnt(0)
	v_cmp_eq_u32_e32 vcc, v0, v1
	s_and_saveexec_b64 s[12:13], vcc
	s_cbranch_execz .LBB0_1212
	s_add_u32 s14, s6, 0x4200
	s_addc_u32 s15, s7, 0
	s_mov_b32 s28, 1
	s_mov_b64 s[18:19], 0
	v_mov_b32_e32 v0, 0
	s_branch .LBB0_1203

.LBB0_1212:
	s_or_b64 exec, exec, s[12:13]
	s_waitcnt vmcnt(0)
	s_waitcnt vmcnt(0)
